# P15 D=2: fused epilogue: first six residual loads issued from the K-loop tail into idle VGPRs; gate/gain second half loaded with the first
# speedup vs baseline: 1.0098x; 1.0098x over previous
; __device__ __forceinline__ void epi_fuse(const f32x4 (&acc)[2][2][4][2], const Args& a, const Job& J, int pm, int pn, int wr, int wc, int fr, int fq, int wid, int lane, LAS unsigned char* pst) {
;     ...
;     const unsigned e0 = (unsigned)((pm * BM + wr * 64 + fr) * DM + col0);
;     typedef _Float16 f16x8 __attribute__((ext_vector_type(8)));
;     f16x8 xr[2][2][2];
; #pragma unroll
;     for (int mm = 0; mm < 2; ++mm)
; #pragma unroll
;         for (int bj = 0; bj < 2; ++bj) xr[0][mm][bj] = *(const f16x8*)(xh + 2u * (e0 + (unsigned)((mm * 16) * DM + bj * HALF)));
; #pragma unroll
;     for (int stp = 0; stp < 4; ++stp) {
;         const int ai = stp >> 1, m0 = (stp & 1) * 2;
;         if (stp + 1 < 4) { const int ai2 = (stp + 1) >> 1, m2 = ((stp + 1) & 1) * 2;
; #pragma unroll
;             for (int mm = 0; mm < 2; ++mm)
; #pragma unroll
;                 for (int bj = 0; bj < 2; ++bj) xr[(stp + 1) & 1][mm][bj] = *(const f16x8*)(xh + 2u * (e0 + (unsigned)((ai2 * HALF + (m2 + mm) * 16) * DM + bj * HALF))); }
.LBB0_282:
	s_add_i32 vcc_lo, s24, 2
	s_cmp_lg_u32 vcc_lo, s13
	s_cbranch_scc1 .Lxp_skip
	s_cmp_lg_u32 s55, 5
	s_cbranch_scc1 .Lxp_skip
	s_cmp_lt_i32 s50, 0
	s_cbranch_scc0 .Lxp_skip
	v_readlane_b32 vcc_lo, v254, 59
	s_lshl_b32 vcc_hi, s78, 8
	s_or_b32 vcc_lo, vcc_lo, vcc_hi
	v_ashrrev_i32_e32 v206, 4, v240
	v_lshl_add_u32 v206, v206, 3, vcc_lo
	v_readlane_b32 vcc_lo, v255, 8
	s_lshl_b32 vcc_hi, s90, 8
	s_add_i32 vcc_lo, vcc_lo, vcc_hi
	v_and_b32_e32 v207, 15, v240
	v_or_b32_e32 v207, vcc_lo, v207
	v_lshl_add_u32 v206, v207, 10, v206
	v_lshlrev_b32_e32 v249, 1, v206
	v_add_u32_e32 v250, 0x8000, v249
	v_add_u32_e32 v251, 0x10000, v249
	v_readlane_b32 vcc_lo, v252, 18
	s_nop 0
	s_cmp_lg_u32 vcc_lo, 0
	v_readlane_b32 vcc_lo, v252, 14
	v_readlane_b32 vcc_hi, v252, 15
	s_cbranch_scc0 .Lxp_nodry
	v_readlane_b32 vcc_lo, v253, 30
	v_readlane_b32 vcc_hi, v253, 31
.Lxp_nodry:
	s_nop 4
	global_load_dwordx4 v[206:209], v249, vcc
	global_load_dwordx4 v[210:213], v249, vcc offset:256
	global_load_dwordx4 v[214:217], v251, vcc
	global_load_dwordx4 v[218:221], v250, vcc
	global_load_dwordx4 v[222:225], v251, vcc offset:256
	global_load_dwordx4 v[200:203], v250, vcc offset:256

; #define LAS __attribute__((address_space(3)))
; __device__ __forceinline__ void epi_fuse(const f32x4 (&acc)[2][2][4][2], const Args& a, const Job& J, int pm, int pn, int wr, int wc, int fr, int fq, int wid, int lane, LAS unsigned char* pst) {
;     ...
;     const int col0 = pn * BM + wc * 32 + 8 * fq;
;     const LAS float* S = (const LAS float*)(pst + 16384);
;     const float* gate = modx + (which == 1 ? 2048 : 5120) + col0; const float* gA = gains + (l * 4 + (which == 1 ? 1 : 3)) * DM + col0;
;     f32x4 gv[2][2];
; #pragma unroll
;     for (int bj = 0; bj < 2; ++bj)
; #pragma unroll
;         for (int n = 0; n < 2; ++n) gv[bj][n] = *(const f32x4*)(gate + bj * HALF + 4 * n) * *(const f32x4*)(gA + bj * HALF + 4 * n);
;     const unsigned e0 = (unsigned)((pm * BM + wr * 64 + fr) * DM + col0);
;     typedef _Float16 f16x8 __attribute__((ext_vector_type(8)));
;     f16x8 xr[2][2][2];
; #pragma unroll
;     for (int mm = 0; mm < 2; ++mm)
; #pragma unroll
;         for (int bj = 0; bj < 2; ++bj) xr[0][mm][bj] = *(const f16x8*)(xh + 2u * (e0 + (unsigned)((mm * 16) * DM + bj * HALF)));
; #pragma unroll
;     for (int stp = 0; stp < 4; ++stp) {
;         const int ai = stp >> 1, m0 = (stp & 1) * 2;
;         if (stp + 1 < 4) { const int ai2 = (stp + 1) >> 1, m2 = ((stp + 1) & 1) * 2;
; #pragma unroll
;             for (int mm = 0; mm < 2; ++mm)
; #pragma unroll
;                 for (int bj = 0; bj < 2; ++bj) xr[(stp + 1) & 1][mm][bj] = *(const f16x8*)(xh + 2u * (e0 + (unsigned)((ai2 * HALF + (m2 + mm) * 16) * DM + bj * HALF))); }
;         __builtin_amdgcn_sched_barrier(0);
; #pragma unroll
;         for (int mm = 0; mm < 2; ++mm) {
;             const int m = m0 + mm;
;             f32x4 t = {0.f, 0.f, 0.f, 0.f};
; #pragma unroll
;             for (int bj = 0; bj < 2; ++bj)
; #pragma unroll
;                 for (int n = 0; n < 2; ++n) {
;                     const f16x8 xq = xr[stp & 1][mm][bj];
;                     const f16x4 xh4 = n == 0 ? (f16x4){xq[0], xq[1], xq[2], xq[3]} : (f16x4){xq[4], xq[5], xq[6], xq[7]};
;                     const f32x4 xv = __builtin_convertvector(xh4, f32x4);
;                     const f32x4 av = acc[ai][bj][m][n], y = gv[bj][n] * av;
; #pragma unroll
;                     for (int e = 0; e < 4; ++e) { t[0] += av[e] * av[e]; t[1] += xv[e] * xv[e]; t[2] += xv[e] * y[e]; t[3] += y[e] * y[e]; }
;                 }
; #pragma unroll
.LBB0_292:
	s_lshr_b32 s12, s90, 3
	v_readlane_b32 s13, v255, 10
	s_add_i32 s12, s12, s13
	s_mul_hi_i32 s13, s12, 0x6000
	s_mulk_i32 s12, 0x6000
	v_readlane_b32 s16, v253, 36
	s_add_u32 s16, s16, s12
	s_addc_u32 s17, s79, s13
	s_lshl_b32 s12, s78, 8
	v_readlane_b32 s13, v254, 59
	s_or_b32 s12, s12, s13
	v_lshl_add_u32 v152, v247, 3, s12
	v_readlane_b32 s12, v255, 35
	s_add_u32 s12, s16, s12
	v_ashrrev_i32_e32 v153, 31, v152
	s_addc_u32 s13, s17, 0
	v_lshlrev_b64 v[170:171], 2, v[152:153]
	v_lshl_add_u64 v[82:83], s[12:13], 0, v[170:171]
	v_readlane_b32 s12, v255, 16
	v_readlane_b32 s13, v255, 17
	s_lshl_b32 s55, s90, 8
	s_nop 0
	v_lshl_add_u64 v[86:87], s[12:13], 0, v[170:171]
	global_load_dwordx4 v[136:139], v[82:83], off offset:16
	global_load_dwordx4 v[140:143], v[82:83], off
	global_load_dwordx4 v[144:147], v[86:87], off offset:16
	global_load_dwordx4 v[148:151], v[86:87], off
	v_readlane_b32 s13, v255, 8
	s_add_i32 s12, s55, s13
	v_or_b32_e32 v80, s12, v248
	v_lshl_add_u32 v85, v80, 10, v152
	global_load_dwordx4 v[152:155], v[82:83], off offset:528
	global_load_dwordx4 v[156:159], v[82:83], off offset:512
	global_load_dwordx4 v[160:163], v[86:87], off offset:528
	global_load_dwordx4 v[164:167], v[86:87], off offset:512
	v_lshlrev_b32_e32 v80, 1, v85
	v_add_u32_e32 v188, 0x100, v80
	v_add_u32_e32 v168, 0x8000, v80
	v_add_u32_e32 v190, 0x8100, v80
	v_add_u32_e32 v172, 0x10000, v80
	v_add_u32_e32 v174, 0x18000, v80
	v_or_b32_e32 v189, s13, v248
	s_waitcnt vmcnt(4)
	v_pk_mul_f32 v[182:183], v[138:139], v[146:147]
	v_pk_mul_f32 v[186:187], v[142:143], v[150:151]
	v_pk_mul_f32 v[184:185], v[140:141], v[148:149]
	v_pk_mul_f32 v[180:181], v[136:137], v[144:145]
	global_load_dwordx4 v[140:143], v174, s[0:1]
	v_add_u32_e32 v136, 0x18100, v80
	s_nop 0
	global_load_dwordx4 v[136:139], v136, s[0:1]
	v_and_b32_e32 v145, 64, v231
	v_xor_b32_e32 v144, 16, v231
	v_add_u32_e32 v145, 64, v145
	v_cmp_lt_i32_e32 vcc, v144, v145
	s_nop 0
	v_cndmask_b32_e32 v144, v231, v144, vcc
	v_lshlrev_b32_e32 v175, 2, v144
	v_xor_b32_e32 v144, 32, v231
	v_cmp_lt_i32_e32 vcc, v144, v145
	s_nop 0
	v_cndmask_b32_e32 v144, v231, v144, vcc
	v_lshlrev_b32_e32 v169, 2, v144
	s_waitcnt vmcnt(2)
	v_pk_mul_f32 v[82:83], v[152:153], v[160:161]
	v_pk_mul_f32 v[178:179], v[158:159], v[166:167]
	v_pk_mul_f32 v[176:177], v[156:157], v[164:165]
	v_pk_mul_f32 v[86:87], v[154:155], v[162:163]
	v_mov_b32_e32 v164, v206
	v_mov_b32_e32 v165, v207
	v_mov_b32_e32 v166, v208
	v_mov_b32_e32 v167, v209
	v_mov_b32_e32 v160, v210
	v_mov_b32_e32 v161, v211
	v_mov_b32_e32 v162, v212
	v_mov_b32_e32 v163, v213
	v_mov_b32_e32 v156, v214
	v_mov_b32_e32 v157, v215
	v_mov_b32_e32 v158, v216
	v_mov_b32_e32 v159, v217
	v_mov_b32_e32 v148, v218
	v_mov_b32_e32 v149, v219
	v_mov_b32_e32 v150, v220
	v_mov_b32_e32 v151, v221
	v_mov_b32_e32 v152, v222
	v_mov_b32_e32 v153, v223
	v_mov_b32_e32 v154, v224
	v_mov_b32_e32 v155, v225
	v_mov_b32_e32 v144, v200
	v_mov_b32_e32 v145, v201
	v_mov_b32_e32 v146, v202
	v_mov_b32_e32 v147, v203
	v_cmp_gt_u32_e32 vcc, 16, v173
	v_mul_f32_e32 v191, v132, v184
	s_waitcnt vmcnt(7)
	v_fma_mix_f32 v192, v191, v164, 0 op_sel_hi:[0,1,0]
	v_mul_f32_e32 v194, v133, v185
	v_cvt_f32_f16_e32 v193, v164
	v_cvt_f32_f16_sdwa v195, v164 dst_sel:DWORD dst_unused:UNUSED_PAD src0_sel:WORD_1
	v_fma_mix_f32 v192, v194, v164, v192 op_sel:[0,1,0] op_sel_hi:[0,1,0]
	v_cvt_f32_f16_e32 v164, v165
	v_cvt_f32_f16_sdwa v165, v165 dst_sel:DWORD dst_unused:UNUSED_PAD src0_sel:WORD_1
	v_pk_mul_f32 v[196:197], v[134:135], v[186:187]
	v_mul_f32_e32 v194, v194, v194
	v_fmac_f32_e32 v194, v191, v191
	v_pk_mul_f32 v[198:199], v[196:197], v[164:165]
	v_pk_mul_f32 v[196:197], v[196:197], v[196:197]
	v_add_f32_e32 v191, v198, v192
	v_add_f32_e32 v191, v199, v191
	v_cvt_f32_f16_e32 v198, v166
	v_cvt_f32_f16_sdwa v199, v166 dst_sel:DWORD dst_unused:UNUSED_PAD src0_sel:WORD_1
	v_add_f32_e32 v166, v196, v194
	v_add_f32_e32 v166, v197, v166
	v_pk_mul_f32 v[196:197], v[128:129], v[180:181]
	v_mov_b32_e32 v194, v133
	v_pk_mul_f32 v[200:201], v[196:197], v[198:199]
	v_pk_mul_f32 v[196:197], v[196:197], v[196:197]
	v_mov_b32_e32 v192, v132
	v_add_f32_e32 v166, v196, v166
	v_pk_mul_f32 v[194:195], v[194:195], v[194:195]
	v_add_f32_e32 v196, v197, v166
	v_pk_fma_f32 v[192:193], v[192:193], v[192:193], v[194:195]
	v_mov_b32_e32 v194, v134
	v_mov_b32_e32 v195, v164
	v_cvt_f32_f16_e32 v166, v167
	v_pk_fma_f32 v[192:193], v[194:195], v[194:195], v[192:193]
	v_mov_b32_e32 v164, v135
	v_pk_fma_f32 v[164:165], v[164:165], v[164:165], v[192:193]
	v_mov_b32_e32 v192, v128
	v_mov_b32_e32 v193, v198
	v_cvt_f32_f16_sdwa v167, v167 dst_sel:DWORD dst_unused:UNUSED_PAD src0_sel:WORD_1
	v_pk_fma_f32 v[164:165], v[192:193], v[192:193], v[164:165]
	v_mov_b32_e32 v198, v129
	v_pk_fma_f32 v[164:165], v[198:199], v[198:199], v[164:165]
	v_mov_b32_e32 v192, v130
	v_mov_b32_e32 v193, v166
	v_add_f32_e32 v191, v200, v191
	v_pk_fma_f32 v[164:165], v[192:193], v[192:193], v[164:165]
	v_pk_mul_f32 v[192:193], v[130:131], v[182:183]
	v_add_f32_e32 v191, v201, v191
	v_pk_mul_f32 v[194:195], v[192:193], v[166:167]
	v_pk_mul_f32 v[192:193], v[192:193], v[192:193]
	v_add_f32_e32 v191, v194, v191
	v_add_f32_e32 v191, v195, v191
	s_waitcnt vmcnt(6)
; #define LAS __attribute__((address_space(3)))
; __device__ __forceinline__ void epi_fuse(const f32x4 (&acc)[2][2][4][2], const Args& a, const Job& J, int pm, int pn, int wr, int wc, int fr, int fq, int wid, int lane, LAS unsigned char* pst) {
;     ...
;             f32x4 t = {0.f, 0.f, 0.f, 0.f};
; #pragma unroll
;             for (int bj = 0; bj < 2; ++bj)
; #pragma unroll
;                 for (int n = 0; n < 2; ++n) {
;                     const f16x8 xq = xr[stp & 1][mm][bj];
;                     const f16x4 xh4 = n == 0 ? (f16x4){xq[0], xq[1], xq[2], xq[3]} : (f16x4){xq[4], xq[5], xq[6], xq[7]};
;                     const f32x4 xv = __builtin_convertvector(xh4, f32x4);
;                     const f32x4 av = acc[ai][bj][m][n], y = gv[bj][n] * av;
; #pragma unroll
;                     for (int e = 0; e < 4; ++e) { t[0] += av[e] * av[e]; t[1] += xv[e] * xv[e]; t[2] += xv[e] * y[e]; t[3] += y[e] * y[e]; }
;                 }
; #pragma unroll
;             for (int e = 0; e < 4; ++e) { t[e] += __shfl_xor(t[e], 16); t[e] += __shfl_xor(t[e], 32); }
;             if (fq == 0) ((LAS f32x4*)pst)[(ai * HALF + wr * 64 + m * 16 + fr) * 4 + wc] = t;
	v_cvt_f32_f16_e32 v194, v160
	v_cvt_f32_f16_sdwa v195, v160 dst_sel:DWORD dst_unused:UNUSED_PAD src0_sel:WORD_1
	v_add_f32_e32 v160, v192, v196
	v_add_f32_e32 v198, v193, v160
	v_pk_mul_f32 v[192:193], v[116:117], v[176:177]
	v_mov_b32_e32 v166, v131
	v_pk_mul_f32 v[196:197], v[192:193], v[194:195]
	v_pk_mul_f32 v[192:193], v[192:193], v[192:193]
	v_add_f32_e32 v160, v196, v191
	v_add_f32_e32 v191, v197, v160
	v_cvt_f32_f16_e32 v160, v161
	v_cvt_f32_f16_sdwa v161, v161 dst_sel:DWORD dst_unused:UNUSED_PAD src0_sel:WORD_1
	v_add_f32_e32 v192, v192, v198
	v_add_f32_e32 v198, v193, v192
	v_pk_mul_f32 v[192:193], v[118:119], v[178:179]
	v_pk_fma_f32 v[164:165], v[166:167], v[166:167], v[164:165]
	v_pk_mul_f32 v[196:197], v[192:193], v[160:161]
	v_pk_mul_f32 v[192:193], v[192:193], v[192:193]
	v_add_f32_e32 v191, v196, v191
	v_add_f32_e32 v191, v197, v191
	v_cvt_f32_f16_e32 v196, v162
	v_cvt_f32_f16_sdwa v197, v162 dst_sel:DWORD dst_unused:UNUSED_PAD src0_sel:WORD_1
	v_add_f32_e32 v162, v192, v198
	v_add_f32_e32 v200, v193, v162
	v_pk_mul_f32 v[192:193], v[112:113], v[82:83]
	v_mov_b32_e32 v166, v116
	v_pk_mul_f32 v[198:199], v[192:193], v[196:197]
	v_mov_b32_e32 v167, v194
	v_add_f32_e32 v162, v198, v191
	v_pk_fma_f32 v[164:165], v[166:167], v[166:167], v[164:165]
	v_mov_b32_e32 v194, v117
	v_add_f32_e32 v162, v199, v162
	v_cvt_f32_f16_e32 v199, v163
	v_pk_fma_f32 v[164:165], v[194:195], v[194:195], v[164:165]
	v_mov_b32_e32 v166, v118
	v_mov_b32_e32 v167, v160
	v_pk_fma_f32 v[164:165], v[166:167], v[166:167], v[164:165]
	v_mov_b32_e32 v160, v119
	v_cvt_f32_f16_sdwa v203, v163 dst_sel:DWORD dst_unused:UNUSED_PAD src0_sel:WORD_1
	v_pk_fma_f32 v[160:161], v[160:161], v[160:161], v[164:165]
	v_mov_b32_e32 v164, v112
	v_mov_b32_e32 v165, v196
	v_pk_mul_f32 v[192:193], v[192:193], v[192:193]
	v_pk_fma_f32 v[160:161], v[164:165], v[164:165], v[160:161]
	v_mov_b32_e32 v196, v113
	v_add_f32_e32 v191, v192, v200
	v_mul_f32_e32 v200, v114, v86
	v_pk_fma_f32 v[160:161], v[196:197], v[196:197], v[160:161]
	v_mov_b32_e32 v198, v114
	v_mov_b32_e32 v201, v115
	v_mov_b32_e32 v166, v199
	v_mov_b32_e32 v167, v87
	v_pk_fma_f32 v[160:161], v[198:199], v[198:199], v[160:161]
	v_mov_b32_e32 v202, v115
	v_pk_mul_f32 v[194:195], v[200:201], v[166:167]
	v_mul_f32_e32 v163, v115, v87
	v_add_f32_e32 v193, v193, v191
	v_pk_fma_f32 v[160:161], v[202:203], v[202:203], v[160:161]
	v_mov_b32_e32 v196, v115
	v_mov_b32_e32 v197, v200
	v_mov_b32_e32 v198, v87
	v_mov_b32_e32 v199, v200
	v_mov_b32_e32 v192, v203
	v_mul_f32_e32 v202, v163, v203
	v_mov_b32_e32 v163, v195
	v_pk_fma_f32 v[192:193], v[196:197], v[198:199], v[192:193]
	v_pk_fma_f32 v[162:163], v[200:201], v[166:167], v[162:163]
	v_pk_mul_f32 v[166:167], v[194:195], v[194:195]
	v_mov_b32_e32 v203, v193
	v_mov_b32_e32 v163, v167
	v_pk_add_f32 v[166:167], v[162:163], v[202:203]
	ds_bpermute_b32 v164, v175, v160
	ds_bpermute_b32 v165, v175, v161
	ds_bpermute_b32 v192, v175, v166
	ds_bpermute_b32 v193, v175, v167
	s_waitcnt lgkmcnt(2)
	v_pk_add_f32 v[160:161], v[160:161], v[164:165]
	ds_bpermute_b32 v162, v169, v160
	s_waitcnt lgkmcnt(1)
	v_pk_add_f32 v[164:165], v[166:167], v[192:193]
	ds_bpermute_b32 v163, v169, v161
	ds_bpermute_b32 v166, v169, v164
	ds_bpermute_b32 v167, v169, v165
	s_and_saveexec_b64 s[12:13], vcc
	s_cbranch_execz .LBB0_294
	v_readlane_b32 s24, v254, 62
	s_waitcnt lgkmcnt(0)
	v_pk_add_f32 v[164:165], v[164:165], v[166:167]
	v_pk_add_f32 v[162:163], v[160:161], v[162:163]
	v_lshl_add_u32 v160, v189, 6, s24
	ds_write_b128 v160, v[162:165]
